# phase_conv cache conversion (inside out_proj phase): 32 serialized load-wait-store round trips batched into two groups of 16 loads in flight
# speedup vs baseline: 1.0066x; 1.0066x over previous
.LBB0_627:
	s_or_b64 exec, exec, s[10:11]
	s_load_dwordx8 s[56:63], s[40:41], 0x10
	s_waitcnt lgkmcnt(0)
	v_lshl_add_u64 v[20:21], s[28:29], 0, v[8:9]
	s_mov_b64 s[10:11], 0x14100000
	v_lshl_add_u64 v[8:9], v[20:21], 0, s[10:11]
	s_mov_b64 s[10:11], 0x14380000
	v_lshl_add_u64 v[10:11], v[20:21], 0, s[10:11]
	v_readlane_b32 s10, v254, 51
	v_readlane_b32 s11, v254, 52
	s_add_u32 s10, s58, s10
	s_addc_u32 s11, s59, s11
	v_lshl_add_u64 v[14:15], s[10:11], 0, v[14:15]
	s_mov_b64 s[10:11], 0x15600000
	v_lshl_add_u64 v[16:17], v[20:21], 0, s[10:11]
	s_mov_b64 s[10:11], 0x15d00000
	v_lshl_add_u64 v[12:13], s[56:57], 0, v[22:23]
	v_lshl_add_u64 v[18:19], s[60:61], 0, v[22:23]
	v_lshl_add_u64 v[20:21], v[20:21], 0, s[10:11]
	v_lshl_add_u64 v[22:23], s[62:63], 0, v[22:23]
	s_mov_b32 s5, 0
	s_movk_i32 s60, 0x5fff
	s_cmp_lt_u32 s14, 0x4000
	s_cbranch_scc1 .LBB0_629
	s_mov_b64 s[16:17], 0x100000
	s_mov_b64 s[18:19], 0x20000
	s_mov_b64 s[38:39], 0x40000
	s_mov_b64 s[50:51], 0x8000
	s_and_saveexec_b64 s[10:11], s[36:37]
	global_load_dwordx4 v[132:135], v[12:13], off
	global_load_dwordx4 v[140:143], v[18:19], off
	global_load_dwordx4 v[144:147], v[22:23], off
	v_lshl_add_u64 v[12:13], v[12:13], 0, s[16:17]
	v_lshl_add_u64 v[18:19], v[18:19], 0, s[16:17]
	v_lshl_add_u64 v[22:23], v[22:23], 0, s[16:17]
	global_load_dwordx4 v[148:151], v[12:13], off
	global_load_dwordx4 v[156:159], v[18:19], off
	global_load_dwordx4 v[160:163], v[22:23], off
	v_lshl_add_u64 v[12:13], v[12:13], 0, s[16:17]
	v_lshl_add_u64 v[18:19], v[18:19], 0, s[16:17]
	v_lshl_add_u64 v[22:23], v[22:23], 0, s[16:17]
	global_load_dwordx4 v[164:167], v[12:13], off
	global_load_dwordx4 v[172:175], v[18:19], off
	global_load_dwordx4 v[176:179], v[22:23], off
	v_lshl_add_u64 v[12:13], v[12:13], 0, s[16:17]
	v_lshl_add_u64 v[18:19], v[18:19], 0, s[16:17]
	v_lshl_add_u64 v[22:23], v[22:23], 0, s[16:17]
	global_load_dwordx4 v[180:183], v[12:13], off
	global_load_dwordx4 v[188:191], v[18:19], off
	global_load_dwordx4 v[192:195], v[22:23], off
	v_lshl_add_u64 v[12:13], v[12:13], 0, s[16:17]
	v_lshl_add_u64 v[18:19], v[18:19], 0, s[16:17]
	v_lshl_add_u64 v[22:23], v[22:23], 0, s[16:17]
	s_or_b64 exec, exec, s[10:11]
	s_and_saveexec_b64 s[10:11], vcc
	global_load_dwordx4 v[136:139], v[14:15], off
	v_lshl_add_u64 v[14:15], v[14:15], 0, s[38:39]
	global_load_dwordx4 v[152:155], v[14:15], off
	v_lshl_add_u64 v[14:15], v[14:15], 0, s[38:39]
	global_load_dwordx4 v[168:171], v[14:15], off
	v_lshl_add_u64 v[14:15], v[14:15], 0, s[38:39]
	global_load_dwordx4 v[184:187], v[14:15], off
	v_lshl_add_u64 v[14:15], v[14:15], 0, s[38:39]
	s_or_b64 exec, exec, s[10:11]
	s_waitcnt vmcnt(0)
	s_and_saveexec_b64 s[10:11], s[36:37]
	v_cvt_pk_bf16_f32 v132, v132, v133
	v_cvt_pk_bf16_f32 v133, v134, v135
	global_store_dwordx2 v[8:9], v[132:133], off
	v_lshl_add_u64 v[8:9], v[8:9], 0, s[18:19]
	v_cvt_pk_bf16_f32 v140, v140, v141
	v_cvt_pk_bf16_f32 v141, v142, v143
	global_store_dwordx2 v[16:17], v[140:141], off
	v_lshl_add_u64 v[16:17], v[16:17], 0, s[18:19]
	v_cvt_pk_bf16_f32 v144, v144, v145
	v_cvt_pk_bf16_f32 v145, v146, v147
	global_store_dwordx2 v[20:21], v[144:145], off
	v_lshl_add_u64 v[20:21], v[20:21], 0, s[18:19]
	v_cvt_pk_bf16_f32 v148, v148, v149
	v_cvt_pk_bf16_f32 v149, v150, v151
	global_store_dwordx2 v[8:9], v[148:149], off
	v_lshl_add_u64 v[8:9], v[8:9], 0, s[18:19]
	v_cvt_pk_bf16_f32 v156, v156, v157
	v_cvt_pk_bf16_f32 v157, v158, v159
	global_store_dwordx2 v[16:17], v[156:157], off
	v_lshl_add_u64 v[16:17], v[16:17], 0, s[18:19]
	v_cvt_pk_bf16_f32 v160, v160, v161
	v_cvt_pk_bf16_f32 v161, v162, v163
	global_store_dwordx2 v[20:21], v[160:161], off
	v_lshl_add_u64 v[20:21], v[20:21], 0, s[18:19]
	v_cvt_pk_bf16_f32 v164, v164, v165
	v_cvt_pk_bf16_f32 v165, v166, v167
	global_store_dwordx2 v[8:9], v[164:165], off
	v_lshl_add_u64 v[8:9], v[8:9], 0, s[18:19]
	v_cvt_pk_bf16_f32 v172, v172, v173
	v_cvt_pk_bf16_f32 v173, v174, v175
	global_store_dwordx2 v[16:17], v[172:173], off
	v_lshl_add_u64 v[16:17], v[16:17], 0, s[18:19]
	v_cvt_pk_bf16_f32 v176, v176, v177
	v_cvt_pk_bf16_f32 v177, v178, v179
	global_store_dwordx2 v[20:21], v[176:177], off
	v_lshl_add_u64 v[20:21], v[20:21], 0, s[18:19]
	v_cvt_pk_bf16_f32 v180, v180, v181
	v_cvt_pk_bf16_f32 v181, v182, v183
	global_store_dwordx2 v[8:9], v[180:181], off
	v_lshl_add_u64 v[8:9], v[8:9], 0, s[18:19]
	v_cvt_pk_bf16_f32 v188, v188, v189
	v_cvt_pk_bf16_f32 v189, v190, v191
	global_store_dwordx2 v[16:17], v[188:189], off
	v_lshl_add_u64 v[16:17], v[16:17], 0, s[18:19]
	v_cvt_pk_bf16_f32 v192, v192, v193
	v_cvt_pk_bf16_f32 v193, v194, v195
	global_store_dwordx2 v[20:21], v[192:193], off
	v_lshl_add_u64 v[20:21], v[20:21], 0, s[18:19]
	s_or_b64 exec, exec, s[10:11]
	s_and_saveexec_b64 s[10:11], vcc
	v_cvt_pk_bf16_f32 v136, v136, v137
	v_cvt_pk_bf16_f32 v137, v138, v139
	global_store_dwordx2 v[10:11], v[136:137], off
	v_lshl_add_u64 v[10:11], v[10:11], 0, s[50:51]
	v_cvt_pk_bf16_f32 v152, v152, v153
	v_cvt_pk_bf16_f32 v153, v154, v155
	global_store_dwordx2 v[10:11], v[152:153], off
	v_lshl_add_u64 v[10:11], v[10:11], 0, s[50:51]
	v_cvt_pk_bf16_f32 v168, v168, v169
	v_cvt_pk_bf16_f32 v169, v170, v171
	global_store_dwordx2 v[10:11], v[168:169], off
	v_lshl_add_u64 v[10:11], v[10:11], 0, s[50:51]
	v_cvt_pk_bf16_f32 v184, v184, v185
	v_cvt_pk_bf16_f32 v185, v186, v187
	global_store_dwordx2 v[10:11], v[184:185], off
	v_lshl_add_u64 v[10:11], v[10:11], 0, s[50:51]
	s_or_b64 exec, exec, s[10:11]
	s_nop 1
	s_and_saveexec_b64 s[10:11], s[36:37]
	global_load_dwordx4 v[132:135], v[12:13], off
	global_load_dwordx4 v[140:143], v[18:19], off
	global_load_dwordx4 v[144:147], v[22:23], off
	v_lshl_add_u64 v[12:13], v[12:13], 0, s[16:17]
	v_lshl_add_u64 v[18:19], v[18:19], 0, s[16:17]
	v_lshl_add_u64 v[22:23], v[22:23], 0, s[16:17]
	global_load_dwordx4 v[148:151], v[12:13], off
	global_load_dwordx4 v[156:159], v[18:19], off
	global_load_dwordx4 v[160:163], v[22:23], off
	v_lshl_add_u64 v[12:13], v[12:13], 0, s[16:17]
	v_lshl_add_u64 v[18:19], v[18:19], 0, s[16:17]
	v_lshl_add_u64 v[22:23], v[22:23], 0, s[16:17]
	global_load_dwordx4 v[164:167], v[12:13], off
	global_load_dwordx4 v[172:175], v[18:19], off
	global_load_dwordx4 v[176:179], v[22:23], off
	v_lshl_add_u64 v[12:13], v[12:13], 0, s[16:17]
	v_lshl_add_u64 v[18:19], v[18:19], 0, s[16:17]
	v_lshl_add_u64 v[22:23], v[22:23], 0, s[16:17]
	global_load_dwordx4 v[180:183], v[12:13], off
	global_load_dwordx4 v[188:191], v[18:19], off
	global_load_dwordx4 v[192:195], v[22:23], off
	v_lshl_add_u64 v[12:13], v[12:13], 0, s[16:17]
	v_lshl_add_u64 v[18:19], v[18:19], 0, s[16:17]
	v_lshl_add_u64 v[22:23], v[22:23], 0, s[16:17]
	s_or_b64 exec, exec, s[10:11]
	s_and_saveexec_b64 s[10:11], vcc
	global_load_dwordx4 v[136:139], v[14:15], off
	v_lshl_add_u64 v[14:15], v[14:15], 0, s[38:39]
	global_load_dwordx4 v[152:155], v[14:15], off
	v_lshl_add_u64 v[14:15], v[14:15], 0, s[38:39]
	global_load_dwordx4 v[168:171], v[14:15], off
	v_lshl_add_u64 v[14:15], v[14:15], 0, s[38:39]
	global_load_dwordx4 v[184:187], v[14:15], off
	v_lshl_add_u64 v[14:15], v[14:15], 0, s[38:39]
	s_or_b64 exec, exec, s[10:11]
	s_waitcnt vmcnt(0)
	s_and_saveexec_b64 s[10:11], s[36:37]
	v_cvt_pk_bf16_f32 v132, v132, v133
	v_cvt_pk_bf16_f32 v133, v134, v135
	global_store_dwordx2 v[8:9], v[132:133], off
	v_lshl_add_u64 v[8:9], v[8:9], 0, s[18:19]
	v_cvt_pk_bf16_f32 v140, v140, v141
	v_cvt_pk_bf16_f32 v141, v142, v143
	global_store_dwordx2 v[16:17], v[140:141], off
	v_lshl_add_u64 v[16:17], v[16:17], 0, s[18:19]
	v_cvt_pk_bf16_f32 v144, v144, v145
	v_cvt_pk_bf16_f32 v145, v146, v147
	global_store_dwordx2 v[20:21], v[144:145], off
	v_lshl_add_u64 v[20:21], v[20:21], 0, s[18:19]
	v_cvt_pk_bf16_f32 v148, v148, v149
	v_cvt_pk_bf16_f32 v149, v150, v151
	global_store_dwordx2 v[8:9], v[148:149], off
	v_lshl_add_u64 v[8:9], v[8:9], 0, s[18:19]
	v_cvt_pk_bf16_f32 v156, v156, v157
	v_cvt_pk_bf16_f32 v157, v158, v159
	global_store_dwordx2 v[16:17], v[156:157], off
	v_lshl_add_u64 v[16:17], v[16:17], 0, s[18:19]
	v_cvt_pk_bf16_f32 v160, v160, v161
	v_cvt_pk_bf16_f32 v161, v162, v163
	global_store_dwordx2 v[20:21], v[160:161], off
	v_lshl_add_u64 v[20:21], v[20:21], 0, s[18:19]
	v_cvt_pk_bf16_f32 v164, v164, v165
	v_cvt_pk_bf16_f32 v165, v166, v167
	global_store_dwordx2 v[8:9], v[164:165], off
	v_lshl_add_u64 v[8:9], v[8:9], 0, s[18:19]
	v_cvt_pk_bf16_f32 v172, v172, v173
	v_cvt_pk_bf16_f32 v173, v174, v175
	global_store_dwordx2 v[16:17], v[172:173], off
	v_lshl_add_u64 v[16:17], v[16:17], 0, s[18:19]
	v_cvt_pk_bf16_f32 v176, v176, v177
	v_cvt_pk_bf16_f32 v177, v178, v179
	global_store_dwordx2 v[20:21], v[176:177], off
	v_lshl_add_u64 v[20:21], v[20:21], 0, s[18:19]
	v_cvt_pk_bf16_f32 v180, v180, v181
	v_cvt_pk_bf16_f32 v181, v182, v183
	global_store_dwordx2 v[8:9], v[180:181], off
	v_lshl_add_u64 v[8:9], v[8:9], 0, s[18:19]
	v_cvt_pk_bf16_f32 v188, v188, v189
	v_cvt_pk_bf16_f32 v189, v190, v191
	global_store_dwordx2 v[16:17], v[188:189], off
	v_lshl_add_u64 v[16:17], v[16:17], 0, s[18:19]
	v_cvt_pk_bf16_f32 v192, v192, v193
	v_cvt_pk_bf16_f32 v193, v194, v195
	global_store_dwordx2 v[20:21], v[192:193], off
	v_lshl_add_u64 v[20:21], v[20:21], 0, s[18:19]
	s_or_b64 exec, exec, s[10:11]
	s_and_saveexec_b64 s[10:11], vcc
	v_cvt_pk_bf16_f32 v136, v136, v137
	v_cvt_pk_bf16_f32 v137, v138, v139
	global_store_dwordx2 v[10:11], v[136:137], off
	v_lshl_add_u64 v[10:11], v[10:11], 0, s[50:51]
	v_cvt_pk_bf16_f32 v152, v152, v153
	v_cvt_pk_bf16_f32 v153, v154, v155
	global_store_dwordx2 v[10:11], v[152:153], off
	v_lshl_add_u64 v[10:11], v[10:11], 0, s[50:51]
	v_cvt_pk_bf16_f32 v168, v168, v169
	v_cvt_pk_bf16_f32 v169, v170, v171
	global_store_dwordx2 v[10:11], v[168:169], off
	v_lshl_add_u64 v[10:11], v[10:11], 0, s[50:51]
	v_cvt_pk_bf16_f32 v184, v184, v185
	v_cvt_pk_bf16_f32 v185, v186, v187
	global_store_dwordx2 v[10:11], v[184:185], off
	v_lshl_add_u64 v[10:11], v[10:11], 0, s[50:51]
	s_or_b64 exec, exec, s[10:11]
	s_mov_b64 s[10:11], 0x40000
	s_mov_b64 s[80:81], 0x20000
	s_mov_b64 s[50:51], 0x100000
	s_mov_b32 s5, 8
	s_branch .LBB0_640
	s_branch .LBB0_629
